# stack + tile-skip bound of the differential units 170 -> 162 (skipped terms are exactly zero in f32: exponent argument below -154)
# speedup vs baseline: 1.0096x; 1.0030x over previous
.LBB0_443:
	s_lshr_b32 s2, s15, 6
	s_ashr_i32 s78, s15, 8
	s_add_i32 s2, s2, s78
	s_and_b32 s10, s2, 3
	s_mul_i32 s3, s78, 23
	s_not_b32 s2, s10
	s_add_i32 s3, s3, s15
	s_lshl_b32 s4, s2, 1
	s_lshl_b32 s2, s78, 5
	s_and_b32 s48, s3, 63
	s_ashr_i32 s3, s2, 31
	s_lshl_b32 s34, s48, 7
	s_lshl_b64 s[2:3], s[2:3], 2
	s_add_u32 s2, s1, s2
	s_addc_u32 s3, s6, s3
	s_lshl_b32 s5, s10, 4
	v_mov_b32_e32 v0, s5
	global_load_dwordx4 v[2:5], v0, s[2:3]
	global_load_dwordx4 v[6:9], v0, s[2:3] offset:64
	v_cvt_f32_i32_e32 v0, s4
	s_ashr_i32 s79, s78, 31
	s_lshl_b64 s[2:3], s[78:79], 13
	v_or_b32_e32 v34, s34, v215
	v_or_b32_e32 v196, s2, v34
	v_mov_b32_e32 v197, s3
	v_lshlrev_b64 v[20:21], 12, v[196:197]
	s_lshl_b32 s57, s10, 7
	s_lshl_b32 s10, s10, 8
	v_lshl_add_u64 v[20:21], s[22:23], 0, v[20:21]
	v_lshl_add_u64 v[20:21], v[20:21], 0, s[10:11]
	s_mov_b32 s39, s11
	v_lshl_add_u64 v[20:21], v[20:21], 0, s[38:39]
	v_mov_b32_e32 v183, v153
	v_lshl_add_u64 v[20:21], v[20:21], 0, v[182:183]
	global_load_dwordx4 v[130:133], v[20:21], off
	global_load_dwordx4 v[134:137], v[20:21], off offset:32
	global_load_dwordx4 v[138:141], v[20:21], off offset:64
	global_load_dwordx4 v[142:145], v[20:21], off offset:96
	v_lshl_add_u64 v[24:25], s[2:3], 0, v[150:151]
	v_lshlrev_b64 v[24:25], 12, v[24:25]
	v_lshl_add_u64 v[24:25], s[22:23], 0, v[24:25]
	v_lshl_add_u64 v[24:25], v[24:25], 0, s[10:11]
	v_lshl_add_u64 v[202:203], v[24:25], 0, v[152:153]
	v_add_u32_e32 v22, s57, v216
	v_mov_b64_e32 v[24:25], s[28:29]
	v_mad_u64_u32 v[26:27], s[2:3], v22, s42, v[24:25]
	v_add_u32_e32 v22, s57, v217
	s_lshl_b64 s[2:3], s[78:79], 14
	v_mad_u64_u32 v[24:25], s[60:61], v22, s42, v[24:25]
	v_lshl_add_u64 v[26:27], v[26:27], 0, s[2:3]
	v_lshl_add_u64 v[24:25], v[24:25], 0, s[2:3]
	v_mov_b32_e32 v181, v153
	s_lshl_b32 s2, s34, 12
	s_mov_b32 s3, s11
	v_mov_b32_e32 v179, v153
	v_lshl_add_u64 v[206:207], v[24:25], 0, v[180:181]
	v_lshl_add_u64 v[24:25], v[202:203], 0, s[2:3]
	s_mov_b32 m0, s7
	v_lshl_add_u64 v[204:205], v[26:27], 0, v[178:179]
	v_lshl_add_u64 v[26:27], v[24:25], 0, s[30:31]
	s_add_i32 s3, s7, 0x2000
	s_or_b32 s2, s34, 64
	global_load_lds_dwordx4 v[26:27], off
	v_lshl_add_u64 v[24:25], v[24:25], 0, s[36:37]
	s_mov_b32 m0, s3
	s_lshl_b32 s60, s2, 12
	s_mov_b32 s61, s11
	global_load_lds_dwordx4 v[24:25], off
	v_lshl_add_u64 v[24:25], v[202:203], 0, s[60:61]
	v_lshl_add_u64 v[26:27], v[24:25], 0, s[30:31]
	s_mov_b32 m0, s43
	global_load_lds_dwordx4 v[26:27], off
	v_lshl_add_u64 v[24:25], v[24:25], 0, s[36:37]
	s_mov_b32 m0, s49
	s_lshl_b32 s62, s34, 1
	global_load_lds_dwordx4 v[24:25], off
	s_mov_b32 s63, s11
	v_lshl_add_u64 v[44:45], v[204:205], 0, s[62:63]
	s_mov_b32 m0, s52
	v_lshl_add_u64 v[46:47], v[206:207], 0, s[62:63]
	global_load_lds_dwordx4 v[44:45], off
	s_mov_b32 m0, s53
	s_nop 0
	global_load_lds_dwordx4 v[46:47], off
	s_waitcnt vmcnt(11)
	v_mov_b32_e32 v10, v2
	s_waitcnt vmcnt(10)
	v_mov_b32_e32 v11, v6
	v_mov_b32_e32 v6, v3
	v_mov_b32_e32 v2, v4
	v_mov_b32_e32 v3, v8
	v_mov_b32_e32 v8, v5
	v_pk_add_f32 v[4:5], v[10:11], v[6:7]
	v_pk_add_f32 v[2:3], v[2:3], v[8:9]
	v_mul_f32_e32 v4, v4, v5
	v_mul_f32_e32 v2, v2, v3
	v_mul_f32_e32 v3, 0x4f800000, v4
	v_cmp_gt_f32_e32 vcc, s35, v4
	v_mul_f32_e32 v5, 0x4f800000, v2
	v_cmp_gt_f32_e64 s[2:3], s35, v2
	v_cndmask_b32_e32 v4, v4, v3, vcc
	v_sqrt_f32_e32 v6, v4
	v_cndmask_b32_e64 v2, v2, v5, s[2:3]
	v_sqrt_f32_e32 v5, v2
	v_exp_f32_e32 v3, v0
	v_add_u32_e32 v0, -1, v6
	v_fma_f32 v10, -v0, v6, v4
	v_add_u32_e32 v8, -1, v5
	v_add_u32_e32 v7, 1, v6
	v_fma_f32 v12, -v8, v5, v2
	v_cmp_ge_f32_e64 s[4:5], 0, v10
	v_add_u32_e32 v9, 1, v5
	v_fma_f32 v11, -v7, v6, v4
	v_cndmask_b32_e64 v0, v6, v0, s[4:5]
	v_cmp_ge_f32_e64 s[4:5], 0, v12
	v_fma_f32 v13, -v9, v5, v2
	s_nop 0
	v_cndmask_b32_e64 v5, v5, v8, s[4:5]
	v_cmp_lt_f32_e64 s[4:5], 0, v11
	s_nop 1
	v_cndmask_b32_e64 v0, v0, v7, s[4:5]
	v_cmp_lt_f32_e64 s[4:5], 0, v13
	v_mul_f32_e32 v6, 0x37800000, v0
	v_cndmask_b32_e32 v0, v0, v6, vcc
	v_cndmask_b32_e64 v5, v5, v9, s[4:5]
	v_mul_f32_e32 v7, 0x37800000, v5
	v_cmp_class_f32_e32 vcc, v4, v222
	v_cndmask_b32_e64 v5, v5, v7, s[2:3]
	s_nop 0
	v_cndmask_b32_e32 v0, v0, v4, vcc
	v_cmp_class_f32_e32 vcc, v2, v222
	s_nop 1
	v_cndmask_b32_e32 v2, v5, v2, vcc
	v_max3_f32 v0, v0, 0, v2
	v_mul_f32_e32 v2, 0x3f828f5c, v0
	v_cmp_gt_f32_e32 vcc, 0x42200000, v2
	s_cmp_lg_u64 vcc, 0
	s_cselect_b32 s98, 1, 0
	s_mov_b32 s99, 0
	v_pk_mul_f32 v[200:201], v[2:3], s[8:9]
	s_nop 0
	v_add_f32_e32 v0, 0x43220000, v200
	v_div_scale_f32 v2, s[2:3], v201, v201, v0
	v_rcp_f32_e32 v3, v2
	v_div_scale_f32 v4, vcc, v0, v201, v0
	s_mov_b32 s2, 0x46000000
	v_fma_f32 v5, -v2, v3, 1.0
	v_fmac_f32_e32 v3, v5, v3
	v_mul_f32_e32 v5, v4, v3
	v_fma_f32 v6, -v2, v5, v4
	v_fmac_f32_e32 v5, v6, v3
	v_fma_f32 v2, -v2, v5, v4
	v_div_fmas_f32 v2, v2, v3, v5
	v_div_fixup_f32 v0, v2, v201, v0
	v_cvt_i32_f32_e32 v2, v0
	v_cmp_gt_f32_e32 vcc, s2, v0
	v_readfirstlane_b32 s2, v2
	s_add_i32 s4, s2, 1
	s_and_b64 s[2:3], vcc, exec
	s_cselect_b32 s2, s4, 0x2000
	s_sub_i32 s3, s34, s2
	s_add_i32 s2, s2, s34
	s_addk_i32 s2, 0x7f
	s_max_i32 s3, s3, 0
	s_min_i32 s2, s2, 0x1fff
	s_lshr_b32 s33, s3, 6
	s_ashr_i32 s4, s2, 6
	s_sub_i32 s2, s4, s33
	s_bitcmp1_b32 s2, 0
	s_cselect_b64 s[2:3], -1, 0
	s_and_b64 vcc, exec, s[2:3]
	s_cbranch_vccnz .LBB0_449
	s_cmpk_gt_i32 s4, 0x7e
	s_mov_b64 s[2:3], -1
	s_cbranch_scc0 .LBB0_446
	s_add_i32 s5, s33, -1
	s_mov_b64 s[2:3], 0
